# launch-time barrier reduced to the wait for all blocks' XCD counts (no publish/acquire handshake before the first phase)
# speedup vs baseline: 1.0053x; 1.0053x over previous
; DEVINL int tidx() { int t = threadIdx.x; asm volatile("" : "+v"(t)); return t; }
; DEVINL unsigned xb_ld(unsigned* p) { return __hip_atomic_load(p, __ATOMIC_RELAXED, __HIP_MEMORY_SCOPE_AGENT); }
; DEVINL unsigned xb_add(unsigned* p, unsigned v) { return __hip_atomic_fetch_add(p, v, __ATOMIC_RELAXED, __HIP_MEMORY_SCOPE_AGENT); }
; #define XB_SPIN(cond, bar) do { unsigned _sp = 0; while (cond) { __builtin_amdgcn_s_sleep(1); \
;     if ((++_sp & 255u) == 0u) { if (xb_ld(&(bar)[XB_TMO])) break; if (_sp > XB_SPIN_CAP) { atomicAdd(&(bar)[XB_TMO], 1u); break; } } } } while (0)
; DEVINL void xcd_barrier(XcdBarrier& b) {
;   asm volatile("s_waitcnt vmcnt(0)" ::: "memory");
;   __syncthreads();
;   if (tidx() == 0) {
;     unsigned* bar = b.bar;
;     __builtin_amdgcn_s_waitcnt(0);
;     if (b.nloc == 0u) xcd_barrier_complete(bar, b.x, b.nloc, b.nx);
;     const unsigned nloc = b.nloc, nx = b.nx;
;     const unsigned old = xb_add(&bar[XB_XSUB(b.x)], 1u);
;     const unsigned gen = old / nloc;
;     if (old + 1u == (gen + 1u) * nloc) {
;       __builtin_amdgcn_fence(__ATOMIC_RELEASE, "agent");
;       asm volatile("s_waitcnt vmcnt(0)" ::: "memory");
;       const unsigned og = xb_add(&bar[XB_TOP], 1u);
;       const unsigned tg = og / nx;
;       if (og + 1u == (tg + 1u) * nx) xb_add(&bar[XB_TOPGEN], 1u);
;       else XB_SPIN(xb_ld(&bar[XB_TOPGEN]) == tg, bar);
;       __builtin_amdgcn_fence(__ATOMIC_ACQUIRE, "agent");
;       xb_add(&bar[XB_XGEN(b.x)], 1u);
;       asm volatile("s_waitcnt vmcnt(0)" ::: "memory");
;     } else {
;       XB_SPIN(xb_ld(&bar[XB_XGEN(b.x)]) == gen, bar);
;       __builtin_amdgcn_fence(__ATOMIC_ACQUIRE, "agent");
;       asm volatile("s_waitcnt vmcnt(0)" ::: "memory");
;     }
; __global__ void __launch_bounds__(256, 2) mega_kernel(Params p) {
;     ...
;   XcdBarrier xb = xcd_barrier_post((unsigned*)(p.ws + OFF_BAR));
;   if (tidx() == 0) { __builtin_amdgcn_fence(__ATOMIC_RELEASE, ""); asm volatile("s_waitcnt vmcnt(0)" ::: "memory"); }
;   xcd_barrier(xb);
.LBB0_21:
	s_mov_b64 s[12:13], exec
	s_lshl_b32 s8, s33, 8
	v_mbcnt_lo_u32_b32 v17, s12, 0
	s_add_u32 s10, s24, s8
	v_mbcnt_hi_u32_b32 v17, s13, v17
	s_mov_b32 s9, 0
	s_addc_u32 s11, s25, 0
	v_cmp_eq_u32_e32 vcc, 0, v17
	s_and_saveexec_b64 s[14:15], vcc
	s_cbranch_execz .LBB0_23
	s_bcnt1_i32_b64 s8, s[12:13]
	v_mov_b32_e32 v18, 0x1000
	v_mov_b32_e32 v19, s8
	v_mov_b32_e32 v18, 0
.LBB0_23:
	s_or_b64 exec, exec, s[14:15]
	s_lshl_b32 s8, s33, 6
	s_cmp_eq_u32 s33, 0
	s_cselect_b64 vcc, -1, 0
	s_cmp_eq_u32 s33, 1
	v_cndmask_b32_e32 v19, 0, v16, vcc
	s_cselect_b64 vcc, -1, 0
	s_cmp_eq_u32 s33, 2
	v_cndmask_b32_e32 v19, v19, v4, vcc
	s_cselect_b64 vcc, -1, 0
	s_cmp_eq_u32 s33, 3
	v_cndmask_b32_e32 v19, v19, v5, vcc
	s_cselect_b64 vcc, -1, 0
	s_cmp_eq_u32 s33, 4
	v_cndmask_b32_e32 v19, v19, v6, vcc
	s_cselect_b64 vcc, -1, 0
	s_cmp_eq_u32 s33, 5
	v_cndmask_b32_e32 v19, v19, v7, vcc
	s_cselect_b64 vcc, -1, 0
	s_cmp_eq_u32 s33, 6
	v_cndmask_b32_e32 v19, v19, v8, vcc
	s_cselect_b64 vcc, -1, 0
	s_cmp_eq_u32 s33, 7
	v_cndmask_b32_e32 v19, v19, v9, vcc
	s_cselect_b64 vcc, -1, 0
	s_cmp_eq_u32 s33, 8
	v_cndmask_b32_e32 v19, v19, v10, vcc
	s_cselect_b64 vcc, -1, 0
	s_cmp_eq_u32 s33, 9
	v_cndmask_b32_e32 v19, v19, v11, vcc
	s_cselect_b64 vcc, -1, 0
	s_cmp_eq_u32 s33, 10
	v_cndmask_b32_e32 v19, v19, v12, vcc
	s_cselect_b64 vcc, -1, 0
	s_cmp_eq_u32 s33, 11
	v_cndmask_b32_e32 v19, v19, v13, vcc
	s_cselect_b64 vcc, -1, 0
	s_cmp_eq_u32 s33, 12
	v_cndmask_b32_e32 v19, v19, v14, vcc
	s_cselect_b64 vcc, -1, 0
	s_cmp_eq_u32 s33, 13
	v_cndmask_b32_e32 v19, v19, v15, vcc
	s_cselect_b64 vcc, -1, 0
	s_cmp_eq_u32 s33, 14
	v_cndmask_b32_e32 v19, v19, v2, vcc
	s_cselect_b64 vcc, -1, 0
	s_cmp_eq_u32 s33, 15
	v_cndmask_b32_e32 v19, v19, v3, vcc
	s_cselect_b64 vcc, -1, 0
	v_cndmask_b32_e32 v19, v19, v1, vcc
	v_cmp_ne_u32_e32 vcc, 0, v16
	v_max_u32_e32 v92, 1, v19
	s_waitcnt vmcnt(0)
	v_readfirstlane_b32 s12, v18
	v_cndmask_b32_e64 v16, 0, 1, vcc
	v_cmp_ne_u32_e32 vcc, 0, v4
	s_nop 1
	v_addc_co_u32_e32 v4, vcc, 0, v16, vcc
	v_cmp_ne_u32_e32 vcc, 0, v5
	s_nop 1
	v_cndmask_b32_e64 v5, 0, 1, vcc
	v_cmp_ne_u32_e32 vcc, 0, v6
	v_cvt_f32_u32_e32 v6, v92
	s_nop 0
	v_addc_co_u32_e32 v4, vcc, v4, v5, vcc
	v_cmp_ne_u32_e32 vcc, 0, v7
	s_nop 1
	v_cndmask_b32_e64 v5, 0, 1, vcc
	v_cmp_ne_u32_e32 vcc, 0, v8
	s_nop 1
	v_addc_co_u32_e32 v4, vcc, v4, v5, vcc
	v_cmp_ne_u32_e32 vcc, 0, v9
	s_nop 1
	v_cndmask_b32_e64 v5, 0, 1, vcc
	v_cmp_ne_u32_e32 vcc, 0, v10
	s_nop 1
	v_addc_co_u32_e32 v4, vcc, v4, v5, vcc
	v_cmp_ne_u32_e32 vcc, 0, v11
	s_nop 1
	v_cndmask_b32_e64 v5, 0, 1, vcc
	v_cmp_ne_u32_e32 vcc, 0, v12
	s_nop 1
	v_addc_co_u32_e32 v4, vcc, v4, v5, vcc
	v_cmp_ne_u32_e32 vcc, 0, v13
	s_nop 1
	v_cndmask_b32_e64 v5, 0, 1, vcc
	v_cmp_ne_u32_e32 vcc, 0, v14
	s_nop 1
	v_addc_co_u32_e32 v4, vcc, v4, v5, vcc
	v_cmp_ne_u32_e32 vcc, 0, v15
	s_nop 1
	v_cndmask_b32_e64 v5, 0, 1, vcc
	v_cmp_ne_u32_e32 vcc, 0, v2
	s_nop 1
	v_addc_co_u32_e32 v2, vcc, v4, v5, vcc
	v_rcp_iflag_f32_e32 v4, v6
	v_cmp_ne_u32_e32 vcc, 0, v3
	s_nop 1
	v_cndmask_b32_e64 v3, 0, 1, vcc
	v_cmp_ne_u32_e32 vcc, 0, v1
	s_nop 1
	v_addc_co_u32_e32 v1, vcc, v2, v3, vcc
	v_mul_f32_e32 v2, 0x4f7ffffe, v4
	v_cvt_u32_f32_e32 v2, v2
	v_sub_u32_e32 v4, 0, v92
	v_add_u32_e32 v3, s12, v17
	v_mul_lo_u32 v4, v4, v2
	v_mul_hi_u32 v4, v2, v4
	v_add_u32_e32 v2, v2, v4
	v_mul_hi_u32 v2, v3, v2
	v_mul_lo_u32 v4, v2, v92
	v_sub_u32_e32 v4, v3, v4
	v_add_u32_e32 v5, 1, v2
	v_cmp_ge_u32_e32 vcc, v4, v92
	v_add_u32_e32 v3, 1, v3
	s_nop 0
	v_cndmask_b32_e32 v2, v2, v5, vcc
	v_sub_u32_e32 v5, v4, v92
	v_cndmask_b32_e32 v4, v4, v5, vcc
	v_add_u32_e32 v5, 1, v2
	v_cmp_ge_u32_e32 vcc, v4, v92
	s_nop 1
	v_cndmask_b32_e32 v2, v2, v5, vcc
	v_mul_lo_u32 v4, v92, v2
	v_add_u32_e32 v4, v4, v92
	v_max_u32_e32 v96, 1, v1
	s_mov_b64 s[12:13], exec
	s_branch .LBB0_57
	v_mov_b32_e32 v3, 0x2000
	global_load_dword v3, v3, s[10:11] offset:1024 sc1
	s_add_u32 s16, s10, 0x2400
	s_addc_u32 s17, s11, 0
	s_waitcnt vmcnt(0)
	v_cmp_eq_u32_e32 vcc, v3, v2
	s_and_saveexec_b64 s[14:15], vcc
	s_cbranch_execz .LBB0_36
	s_mov_b32 s30, 1
	s_mov_b64 s[18:19], 0
	v_mov_b32_e32 v3, 0
	s_branch .LBB0_27
